# speedup vs baseline: 1.0014x; 1.0014x over previous
; template <int EPI, int PN>
; __device__ void gemm_phase(const Params& p, const u16* __restrict__ A, const u16* __restrict__ Bt, int nNt, char* smem) {
;     ...
;     for (int kt = 0; kt < 32; ++kt) {
;       asm volatile("s_waitcnt vmcnt(0)" ::: "memory");
;       __builtin_amdgcn_s_barrier();
;       const u16* Ab = ring + (kt & 1) * STG;
;       const u16* Bb = Ab + 16384;
;       u16* st = ring + ((kt + 1) & 1) * STG;
;       const bool pre = (kt + 1 < 32);
;       s16x8 af[2][4], bf[2][2];
;       auto ldfrag = [&](int ks, int slot) {
; #pragma unroll
;         for (int i = 0; i < 4; ++i) {
;           const int row = wr * 128 + i * 32 + lr;
;           af[slot][i] = *(const s16x8*)(Ab + row * 64 + (((ks * 2 + lh) ^ ((row >> 1) & 7)) * 8));
;         }
; #pragma unroll
;         for (int j = 0; j < 2; ++j) {
;           const int rowb = nh * 128 + wc * 64 + j * 32 + lr;
;           bf[slot][j] = *(const s16x8*)(Bb + rowb * 64 + (((ks * 2 + lh) ^ ((rowb >> 1) & 7)) * 8));
;         }
;       };
;       ldfrag(0, 0);
;       ldfrag(1, 1);
;       __builtin_amdgcn_sched_barrier(0);
; #pragma unroll
;       for (int ks = 0; ks < 4; ++ks) {
;         const int slot = ks & 1;
; #pragma unroll
;         for (int i = 0; i < 4; ++i) {
;           acc[i][0] = mfma32(af[slot][i], bf[slot][0], acc[i][0]);
;           acc[i][1] = mfma32(af[slot][i], bf[slot][1], acc[i][1]);
;           __builtin_amdgcn_sched_barrier(0);
;           if (pre && (i & 1) == 0) {
;             const int pi = ks * 2 + (i >> 1);
;             if (pi < 4) glds16(Ag0 + (size_t)pi * 64 * LDK + (kt + 1) * 64, st + (srow + 64 * pi) * 64 + sch * 8);
;             else glds16(Bg0 + (size_t)(pi - 4) * 64 * LDK + (kt + 1) * 64, st + 16384 + (srow + 64 * (pi - 4)) * 64 + sch * 8);
;             __builtin_amdgcn_sched_barrier(0);
;           }
;         }
;         if (ks + 2 < 4) { ldfrag(ks + 2, slot); __builtin_amdgcn_sched_barrier(0); }
;       }
.Lrot666_loop:
	s_add_i32 s18, s17, 0xffff8000
	s_and_b32 s18, s18, 0x8000
	s_lshl_b32 s18, s18, 1
	v_lshl_or_b32 v128, v143, 1, s18
	v_lshl_add_u32 v166, v147, 1, s18
	s_and_b32 s98, s17, 0x8000
	s_lshl_b32 s98, s98, 1
	s_waitcnt lgkmcnt(7)
	v_mfma_f32_32x32x16_bf16 v[112:127], v[162:165], v[180:183], v[112:127]
	v_add3_u32 v148, s98, v224, v156
	s_waitcnt lgkmcnt(6)
	v_mfma_f32_32x32x16_bf16 v[48:63], v[162:165], v[184:187], v[48:63]
	v_readfirstlane_b32 s100, v148
	s_mov_b32 s19, m0
	s_add_i32 m0, s100, 0x8000
	s_nop 0
	global_load_lds_dwordx4 v[160:161], off
	v_mfma_f32_32x32x16_bf16 v[96:111], v[168:171], v[180:183], v[96:111]
	v_lshl_add_u64 v[162:163], v[160:161], 0, s[4:5]
	s_add_i32 m0, s100, 0xa000
	s_nop 0
	global_load_lds_dwordx4 v[162:163], off
	v_mfma_f32_32x32x16_bf16 v[32:47], v[168:171], v[184:187], v[32:47]
	v_lshl_add_u64 v[164:165], v[160:161], 0, s[6:7]
	s_add_i32 m0, s100, 0xc000
	s_nop 0
	global_load_lds_dwordx4 v[164:165], off
	v_mfma_f32_32x32x16_bf16 v[80:95], v[172:175], v[180:183], v[80:95]
	v_lshl_add_u64 v[162:163], v[160:161], 0, s[8:9]
	s_add_i32 m0, s100, 0xe000
	s_nop 0
	global_load_lds_dwordx4 v[162:163], off
	s_mov_b32 m0, s19
	v_mfma_f32_32x32x16_bf16 v[16:31], v[172:175], v[184:187], v[16:31]
	v_mfma_f32_32x32x16_bf16 v[64:79], v[176:179], v[180:183], v[64:79]
	v_mfma_f32_32x32x16_bf16 v[0:15], v[176:179], v[184:187], v[0:15]
	v_lshl_add_u64 v[160:161], v[160:161], 0, s[10:11]
	v_add_u32_e32 v176, v128, v236
	ds_read_b128 v[162:165], v176
	ds_read_b128 v[168:171], v176 offset:4096
	ds_read_b128 v[172:175], v176 offset:8192
	ds_read_b128 v[176:179], v176 offset:12288
	v_add_u32_e32 v184, v166, v236
	ds_read_b128 v[180:183], v184 offset:32768
	ds_read_b128 v[184:187], v184 offset:36864
	s_waitcnt lgkmcnt(7)
	v_mfma_f32_32x32x16_bf16 v[112:127], v[188:191], v[204:207], v[112:127]
	s_waitcnt lgkmcnt(6)
	v_mfma_f32_32x32x16_bf16 v[48:63], v[188:191], v[208:211], v[48:63]
	v_mfma_f32_32x32x16_bf16 v[96:111], v[192:195], v[204:207], v[96:111]
	v_mfma_f32_32x32x16_bf16 v[32:47], v[192:195], v[208:211], v[32:47]
	v_mfma_f32_32x32x16_bf16 v[80:95], v[196:199], v[204:207], v[80:95]
	v_mfma_f32_32x32x16_bf16 v[16:31], v[196:199], v[208:211], v[16:31]
	v_mfma_f32_32x32x16_bf16 v[64:79], v[200:203], v[204:207], v[64:79]
	v_mfma_f32_32x32x16_bf16 v[0:15], v[200:203], v[208:211], v[0:15]
	v_add_u32_e32 v128, v128, v237
	ds_read_b128 v[188:191], v128
	ds_read_b128 v[192:195], v128 offset:4096
	ds_read_b128 v[196:199], v128 offset:8192
	ds_read_b128 v[200:203], v128 offset:12288
	v_add_u32_e32 v128, v166, v237
	ds_read_b128 v[204:207], v128 offset:32768
	ds_read_b128 v[208:211], v128 offset:36864
	s_waitcnt lgkmcnt(7)
	v_mfma_f32_32x32x16_bf16 v[112:127], v[162:165], v[180:183], v[112:127]
	s_waitcnt lgkmcnt(6)
	v_mfma_f32_32x32x16_bf16 v[48:63], v[162:165], v[184:187], v[48:63]
	v_mfma_f32_32x32x16_bf16 v[96:111], v[168:171], v[180:183], v[96:111]
	v_mfma_f32_32x32x16_bf16 v[32:47], v[168:171], v[184:187], v[32:47]
	v_mfma_f32_32x32x16_bf16 v[80:95], v[172:175], v[180:183], v[80:95]
	v_mfma_f32_32x32x16_bf16 v[16:31], v[172:175], v[184:187], v[16:31]
	v_mfma_f32_32x32x16_bf16 v[64:79], v[176:179], v[180:183], v[64:79]
	v_mfma_f32_32x32x16_bf16 v[0:15], v[176:179], v[184:187], v[0:15]
	v_lshl_or_b32 v212, v143, 1, s98
	v_lshl_add_u32 v213, v147, 1, s98
	v_add_u32_e32 v149, v212, v234
	v_add_u32_e32 v148, v213, v234
	s_waitcnt vmcnt(0) lgkmcnt(0)
	s_barrier
	ds_read_b128 v[162:165], v149
	ds_read_b128 v[168:171], v149 offset:4096
	ds_read_b128 v[172:175], v149 offset:8192
	ds_read_b128 v[176:179], v149 offset:12288
	ds_read_b128 v[180:183], v148 offset:32768
	ds_read_b128 v[184:187], v148 offset:36864
	v_add3_u32 v148, s18, v224, v156
	v_mfma_f32_32x32x16_bf16 v[112:127], v[188:191], v[204:207], v[112:127]
	v_readfirstlane_b32 s99, v148
	s_mov_b32 s19, m0
	s_mov_b32 m0, s99
	s_nop 0
	global_load_lds_dwordx4 v[158:159], off
	v_mfma_f32_32x32x16_bf16 v[48:63], v[188:191], v[208:211], v[48:63]
	v_lshl_add_u64 v[188:189], v[158:159], 0, s[4:5]
	s_add_i32 m0, s99, 0x2000
	s_nop 0
	global_load_lds_dwordx4 v[188:189], off
	v_mfma_f32_32x32x16_bf16 v[96:111], v[192:195], v[204:207], v[96:111]
	v_lshl_add_u64 v[190:191], v[158:159], 0, s[6:7]
	s_add_i32 m0, s99, 0x4000
	s_nop 0
	global_load_lds_dwordx4 v[190:191], off
	v_mfma_f32_32x32x16_bf16 v[32:47], v[192:195], v[208:211], v[32:47]
	v_lshl_add_u64 v[188:189], v[158:159], 0, s[8:9]
	s_add_i32 m0, s99, 0x6000
	s_nop 0
	global_load_lds_dwordx4 v[188:189], off
	s_mov_b32 m0, s19
	v_mfma_f32_32x32x16_bf16 v[80:95], v[196:199], v[204:207], v[80:95]
	v_mfma_f32_32x32x16_bf16 v[16:31], v[196:199], v[208:211], v[16:31]
	v_mfma_f32_32x32x16_bf16 v[64:79], v[200:203], v[204:207], v[64:79]
	v_mfma_f32_32x32x16_bf16 v[0:15], v[200:203], v[208:211], v[0:15]
	v_add_u32_e32 v149, v212, v235
	v_add_u32_e32 v148, v213, v235
	ds_read_b128 v[188:191], v149
	ds_read_b128 v[192:195], v149 offset:4096
	ds_read_b128 v[196:199], v149 offset:8192
	ds_read_b128 v[200:203], v149 offset:12288
	ds_read_b128 v[204:207], v148 offset:32768
	ds_read_b128 v[208:211], v148 offset:36864
	s_add_i32 s17, s17, 0x8000
	v_lshl_add_u64 v[158:159], v[158:159], 0, s[10:11]
	s_cmp_eq_u32 s17, 0xf8000
	s_cbranch_scc0 .Lrot666_loop
; template <int EPI, int PN>
; __device__ void gemm_phase(const Params& p, const u16* __restrict__ A, const u16* __restrict__ Bt, int nNt, char* smem) {
;     ...
;   for (int q = jb;; q += NJ) {
;     const int pl = q / (4 * PN), w = q % (4 * PN);
;     const int gp = pl * 8 + xcd;
;     if (gp >= npatch) break;
;     const int mt = (gp / npn) * 4 + (w & 3), nt = (gp % npn) * PN + (w >> 2);
;     const int gch = sch ^ ((srow >> 1) & 7);
;     const u16* Ag0 = A + (size_t)(mt * 256 + srow) * LDK + gch * 8;
;     const u16* Bg0 = Bt + (size_t)(nt * 256 + srow) * LDK + gch * 8;
;     ...
;     for (int kt = 0; kt < 32; ++kt) {
;       asm volatile("s_waitcnt vmcnt(0)" ::: "memory");
;       __builtin_amdgcn_s_barrier();
;       const u16* Ab = ring + (kt & 1) * STG;
;       const u16* Bb = Ab + 16384;
;       u16* st = ring + ((kt + 1) & 1) * STG;
;       const bool pre = (kt + 1 < 32);
;       s16x8 af[2][4], bf[2][2];
;       auto ldfrag = [&](int ks, int slot) {
; #pragma unroll
;         for (int i = 0; i < 4; ++i) {
;           const int row = wr * 128 + i * 32 + lr;
;           af[slot][i] = *(const s16x8*)(Ab + row * 64 + (((ks * 2 + lh) ^ ((row >> 1) & 7)) * 8));
;         }
; #pragma unroll
;         for (int j = 0; j < 2; ++j) {
;           const int rowb = nh * 128 + wc * 64 + j * 32 + lr;
;           bf[slot][j] = *(const s16x8*)(Bb + rowb * 64 + (((ks * 2 + lh) ^ ((rowb >> 1) & 7)) * 8));
;         }
;       };
;       ldfrag(0, 0);
;       ldfrag(1, 1);
;       __builtin_amdgcn_sched_barrier(0);
; #pragma unroll
;       for (int ks = 0; ks < 4; ++ks) {
;         const int slot = ks & 1;
; #pragma unroll
;         for (int i = 0; i < 4; ++i) {
;           acc[i][0] = mfma32(af[slot][i], bf[slot][0], acc[i][0]);
;           acc[i][1] = mfma32(af[slot][i], bf[slot][1], acc[i][1]);
;           __builtin_amdgcn_sched_barrier(0);
;           if (pre && (i & 1) == 0) {
;             const int pi = ks * 2 + (i >> 1);
;             if (pi < 4) glds16(Ag0 + (size_t)pi * 64 * LDK + (kt + 1) * 64, st + (srow + 64 * pi) * 64 + sch * 8);
;             else glds16(Bg0 + (size_t)(pi - 4) * 64 * LDK + (kt + 1) * 64, st + 16384 + (srow + 64 * (pi - 4)) * 64 + sch * 8);
;             __builtin_amdgcn_sched_barrier(0);
;           }
;         }
;         if (ks + 2 < 4) { ldfrag(ks + 2, slot); __builtin_amdgcn_sched_barrier(0); }
;       }
	s_add_i32 s18, s17, 0xffff8000
	s_and_b32 s18, s18, 0x8000
	s_lshl_b32 s18, s18, 1
	v_lshl_or_b32 v128, v143, 1, s18
	v_lshl_add_u32 v166, v147, 1, s18
	s_and_b32 s98, s17, 0x8000
	s_lshl_b32 s98, s98, 1
	s_waitcnt lgkmcnt(7)
	v_mfma_f32_32x32x16_bf16 v[112:127], v[162:165], v[180:183], v[112:127]
	v_add3_u32 v148, s98, v224, v156
	s_waitcnt lgkmcnt(6)
	v_mfma_f32_32x32x16_bf16 v[48:63], v[162:165], v[184:187], v[48:63]
	v_readfirstlane_b32 s100, v148
	s_mov_b32 s19, m0
	s_add_i32 m0, s100, 0x8000
	s_nop 0
	global_load_lds_dwordx4 v[160:161], off
	v_mfma_f32_32x32x16_bf16 v[96:111], v[168:171], v[180:183], v[96:111]
	v_lshl_add_u64 v[162:163], v[160:161], 0, s[4:5]
	s_add_i32 m0, s100, 0xa000
	s_nop 0
	global_load_lds_dwordx4 v[162:163], off
	v_mfma_f32_32x32x16_bf16 v[32:47], v[168:171], v[184:187], v[32:47]
	v_lshl_add_u64 v[164:165], v[160:161], 0, s[6:7]
	s_add_i32 m0, s100, 0xc000
	s_nop 0
	global_load_lds_dwordx4 v[164:165], off
	v_mfma_f32_32x32x16_bf16 v[80:95], v[172:175], v[180:183], v[80:95]
	v_lshl_add_u64 v[162:163], v[160:161], 0, s[8:9]
	s_add_i32 m0, s100, 0xe000
	s_nop 0
	global_load_lds_dwordx4 v[162:163], off
	s_mov_b32 m0, s19
	v_mfma_f32_32x32x16_bf16 v[16:31], v[172:175], v[184:187], v[16:31]
	v_mfma_f32_32x32x16_bf16 v[64:79], v[176:179], v[180:183], v[64:79]
	v_mfma_f32_32x32x16_bf16 v[0:15], v[176:179], v[184:187], v[0:15]
	v_lshl_add_u64 v[160:161], v[160:161], 0, s[10:11]
	v_add_u32_e32 v176, v128, v236
	ds_read_b128 v[162:165], v176
	ds_read_b128 v[168:171], v176 offset:4096
	ds_read_b128 v[172:175], v176 offset:8192
	ds_read_b128 v[176:179], v176 offset:12288
	v_add_u32_e32 v184, v166, v236
	ds_read_b128 v[180:183], v184 offset:32768
	ds_read_b128 v[184:187], v184 offset:36864
	s_waitcnt lgkmcnt(7)
	v_mfma_f32_32x32x16_bf16 v[112:127], v[188:191], v[204:207], v[112:127]
	s_waitcnt lgkmcnt(6)
	v_mfma_f32_32x32x16_bf16 v[48:63], v[188:191], v[208:211], v[48:63]
	v_mfma_f32_32x32x16_bf16 v[96:111], v[192:195], v[204:207], v[96:111]
	v_mfma_f32_32x32x16_bf16 v[32:47], v[192:195], v[208:211], v[32:47]
	v_mfma_f32_32x32x16_bf16 v[80:95], v[196:199], v[204:207], v[80:95]
	v_mfma_f32_32x32x16_bf16 v[16:31], v[196:199], v[208:211], v[16:31]
	v_mfma_f32_32x32x16_bf16 v[64:79], v[200:203], v[204:207], v[64:79]
	v_mfma_f32_32x32x16_bf16 v[0:15], v[200:203], v[208:211], v[0:15]
	v_add_u32_e32 v128, v128, v237
	ds_read_b128 v[188:191], v128
	ds_read_b128 v[192:195], v128 offset:4096
	ds_read_b128 v[196:199], v128 offset:8192
	ds_read_b128 v[200:203], v128 offset:12288
	v_add_u32_e32 v128, v166, v237
	ds_read_b128 v[204:207], v128 offset:32768
	ds_read_b128 v[208:211], v128 offset:36864
	v_readlane_b32 s98, v254, 28
	v_readlane_b32 s99, v254, 24
	s_nop 1
	s_add_i32 s98, s16, s98
	s_lshr_b32 s100, s98, 5
	s_lshl_b32 s101, s100, 3
	s_or_b32 s101, s101, s99
	s_cmp_lt_i32 s101, 32
	s_cselect_b32 s98, s98, s16
	s_lshr_b32 s100, s98, 5
	s_and_b32 s101, s98, 31
	s_lshl_b32 s100, s100, 3
	s_or_b32 s100, s100, s99
	s_and_b32 s99, s101, 3
	s_lshl_b32 s100, s100, 2
	s_or_b32 s100, s100, s99
	s_ashr_i32 s101, s101, 2
	v_readfirstlane_b32 s98, v252
	s_nop 1
	s_lshr_b32 s98, s98, 6
	s_cmp_lt_u32 s98, 4
	s_cselect_b32 s100, s100, s101
	s_and_b32 s99, s98, 3
	s_lshl_b32 s99, s99, 6
	s_lshl_b32 s100, s100, 8
	s_add_i32 s100, s100, s99
	v_add_u32_e32 v212, s100, v135
	v_mul_lo_u32 v212, v212, s2
	v_readlane_b32 s100, v253, 45
	v_readlane_b32 s101, v253, 46
	v_readlane_b32 s96, v253, 33
	v_readlane_b32 s97, v253, 34
	s_nop 1
	s_cmp_lt_u32 s98, 4
	s_cselect_b64 s[100:101], s[100:101], s[96:97]
	s_nop 3
	global_load_dword v213, v212, s[100:101]
	global_load_dword v213, v212, s[100:101] offset:128
	s_waitcnt lgkmcnt(7)
	v_mfma_f32_32x32x16_bf16 v[112:127], v[162:165], v[180:183], v[112:127]
	s_waitcnt lgkmcnt(6)
	v_mfma_f32_32x32x16_bf16 v[48:63], v[162:165], v[184:187], v[48:63]
	v_mfma_f32_32x32x16_bf16 v[96:111], v[168:171], v[180:183], v[96:111]
	v_mfma_f32_32x32x16_bf16 v[32:47], v[168:171], v[184:187], v[32:47]
	v_mfma_f32_32x32x16_bf16 v[80:95], v[172:175], v[180:183], v[80:95]
	v_mfma_f32_32x32x16_bf16 v[16:31], v[172:175], v[184:187], v[16:31]
	v_mfma_f32_32x32x16_bf16 v[64:79], v[176:179], v[180:183], v[64:79]
	v_mfma_f32_32x32x16_bf16 v[0:15], v[176:179], v[184:187], v[0:15]
	s_waitcnt lgkmcnt(1)
	v_mfma_f32_32x32x16_bf16 v[112:127], v[188:191], v[204:207], v[112:127]
	s_waitcnt lgkmcnt(0)
	v_mfma_f32_32x32x16_bf16 v[48:63], v[188:191], v[208:211], v[48:63]
	v_mfma_f32_32x32x16_bf16 v[96:111], v[192:195], v[204:207], v[96:111]
	v_mfma_f32_32x32x16_bf16 v[32:47], v[192:195], v[208:211], v[32:47]
	v_mfma_f32_32x32x16_bf16 v[80:95], v[196:199], v[204:207], v[80:95]
	v_mfma_f32_32x32x16_bf16 v[16:31], v[196:199], v[208:211], v[16:31]
	v_mfma_f32_32x32x16_bf16 v[64:79], v[200:203], v[204:207], v[64:79]
	v_mfma_f32_32x32x16_bf16 v[0:15], v[200:203], v[208:211], v[0:15]
	s_waitcnt vmcnt(2)
	s_barrier
; __device__ __forceinline__ int accrow(int reg, int lh) { return (reg & 3) + 8 * (reg >> 2) + 4 * lh; }
; template <int EPI, int PN>
; __device__ void gemm_phase(const Params& p, const u16* __restrict__ A, const u16* __restrict__ Bt, int nNt, char* smem) {
;     ...
;       ldfrag(0, 0);
;       ldfrag(1, 1);
;       __builtin_amdgcn_sched_barrier(0);
; #pragma unroll
;       for (int ks = 0; ks < 4; ++ks) {
;         const int slot = ks & 1;
; #pragma unroll
;         for (int i = 0; i < 4; ++i) {
;           acc[i][0] = mfma32(af[slot][i], bf[slot][0], acc[i][0]);
;           acc[i][1] = mfma32(af[slot][i], bf[slot][1], acc[i][1]);
;           __builtin_amdgcn_sched_barrier(0);
;           if (pre && (i & 1) == 0) {
;             const int pi = ks * 2 + (i >> 1);
;             if (pi < 4) glds16(Ag0 + (size_t)pi * 64 * LDK + (kt + 1) * 64, st + (srow + 64 * pi) * 64 + sch * 8);
;             else glds16(Bg0 + (size_t)(pi - 4) * 64 * LDK + (kt + 1) * 64, st + 16384 + (srow + 64 * (pi - 4)) * 64 + sch * 8);
;             __builtin_amdgcn_sched_barrier(0);
;           }
;         }
;         if (ks + 2 < 4) { ldfrag(ks + 2, slot); __builtin_amdgcn_sched_barrier(0); }
;       }
;     }
;     __syncthreads();
;     int mte = __builtin_amdgcn_readfirstlane(mt), nte = __builtin_amdgcn_readfirstlane(nt), lrE = lr, lhE = lh, laneE = lane;
;     asm volatile("" : "+s"(mte), "+s"(nte), "+v"(lrE), "+v"(lhE), "+v"(laneE));
;     unsigned char* et = (unsigned char*)smem + wv * 18432;
;     const int col0 = nte * 256 + nh * 128 + wc * 64;
;     const size_t row0 = (size_t)mte * 256 + wr * 128;
;     if (EPI == 1) {
; #pragma unroll
;       for (int j = 0; j < 2; ++j) {
; #pragma unroll
;         for (int i = 0; i < 4; ++i)
; #pragma unroll
;           for (int r = 0; r < 16; ++r) *(float*)(et + (i * 32 + accrow(r, lhE)) * 144 + lrE * 4) = acc[i][j][r];
	ds_read_b128 v[158:161], v226
	ds_read_b128 v[162:165], v226 offset:4096
	ds_read_b128 v[168:171], v226 offset:8192
	ds_read_b128 v[172:175], v226 offset:12288
	ds_read_b128 v[176:179], v227
	ds_read_b128 v[180:183], v227 offset:4096
	ds_read_b128 v[184:187], v228
	ds_read_b128 v[188:191], v228 offset:4096
	ds_read_b128 v[192:195], v228 offset:8192
	ds_read_b128 v[196:199], v228 offset:12288
	ds_read_b128 v[200:203], v229
	ds_read_b128 v[204:207], v229 offset:4096
	s_waitcnt lgkmcnt(7)
	v_mfma_f32_32x32x16_bf16 v[112:127], v[158:161], v[176:179], v[112:127]
	s_waitcnt lgkmcnt(6)
	v_mfma_f32_32x32x16_bf16 v[48:63], v[158:161], v[180:183], v[48:63]
	v_mfma_f32_32x32x16_bf16 v[96:111], v[162:165], v[176:179], v[96:111]
	v_mfma_f32_32x32x16_bf16 v[32:47], v[162:165], v[180:183], v[32:47]
	v_mfma_f32_32x32x16_bf16 v[80:95], v[168:171], v[176:179], v[80:95]
	v_mfma_f32_32x32x16_bf16 v[16:31], v[168:171], v[180:183], v[16:31]
	v_mfma_f32_32x32x16_bf16 v[64:79], v[172:175], v[176:179], v[64:79]
	v_mfma_f32_32x32x16_bf16 v[0:15], v[172:175], v[180:183], v[0:15]
	ds_read_b128 v[158:161], v230
	ds_read_b128 v[162:165], v230 offset:4096
	ds_read_b128 v[168:171], v230 offset:8192
	ds_read_b128 v[172:175], v230 offset:12288
	ds_read_b128 v[176:179], v231
	ds_read_b128 v[180:183], v231 offset:4096
	s_waitcnt lgkmcnt(7)
	v_mfma_f32_32x32x16_bf16 v[112:127], v[184:187], v[200:203], v[112:127]
	s_waitcnt lgkmcnt(6)
	v_mfma_f32_32x32x16_bf16 v[48:63], v[184:187], v[204:207], v[48:63]
	v_mfma_f32_32x32x16_bf16 v[96:111], v[188:191], v[200:203], v[96:111]
	v_mfma_f32_32x32x16_bf16 v[32:47], v[188:191], v[204:207], v[32:47]
	v_mfma_f32_32x32x16_bf16 v[80:95], v[192:195], v[200:203], v[80:95]
	v_mfma_f32_32x32x16_bf16 v[16:31], v[192:195], v[204:207], v[16:31]
	v_mfma_f32_32x32x16_bf16 v[64:79], v[196:199], v[200:203], v[64:79]
	v_mfma_f32_32x32x16_bf16 v[0:15], v[196:199], v[204:207], v[0:15]
	ds_read_b128 v[184:187], v232
	ds_read_b128 v[188:191], v232 offset:4096
	ds_read_b128 v[192:195], v232 offset:8192
	ds_read_b128 v[196:199], v232 offset:12288
	ds_read_b128 v[200:203], v233
	ds_read_b128 v[204:207], v233 offset:4096
	s_waitcnt lgkmcnt(7)
	v_mfma_f32_32x32x16_bf16 v[112:127], v[158:161], v[176:179], v[112:127]
	s_waitcnt lgkmcnt(6)
	v_mfma_f32_32x32x16_bf16 v[48:63], v[158:161], v[180:183], v[48:63]
	v_mfma_f32_32x32x16_bf16 v[96:111], v[162:165], v[176:179], v[96:111]
	v_mfma_f32_32x32x16_bf16 v[32:47], v[162:165], v[180:183], v[32:47]
	v_mfma_f32_32x32x16_bf16 v[80:95], v[168:171], v[176:179], v[80:95]
	v_mfma_f32_32x32x16_bf16 v[16:31], v[168:171], v[180:183], v[16:31]
	v_mfma_f32_32x32x16_bf16 v[64:79], v[172:175], v[176:179], v[64:79]
	v_mfma_f32_32x32x16_bf16 v[0:15], v[172:175], v[180:183], v[0:15]
	s_waitcnt lgkmcnt(1)
	v_mfma_f32_32x32x16_bf16 v[112:127], v[184:187], v[200:203], v[112:127]
	s_waitcnt lgkmcnt(0)
	v_mfma_f32_32x32x16_bf16 v[48:63], v[184:187], v[204:207], v[48:63]
	v_mfma_f32_32x32x16_bf16 v[96:111], v[188:191], v[200:203], v[96:111]
	v_mfma_f32_32x32x16_bf16 v[32:47], v[188:191], v[204:207], v[32:47]
	v_mfma_f32_32x32x16_bf16 v[80:95], v[192:195], v[200:203], v[80:95]
	v_mfma_f32_32x32x16_bf16 v[16:31], v[192:195], v[204:207], v[16:31]
	v_mfma_f32_32x32x16_bf16 v[64:79], v[196:199], v[200:203], v[64:79]
	v_mfma_f32_32x32x16_bf16 v[0:15], v[196:199], v[204:207], v[0:15]
	v_mov_b32_e32 v128, v139
	v_mov_b32_e32 v148, v137
	v_mov_b32_e32 v218, v135
	s_barrier
	v_readlane_b32 s52, v253, 7
	v_lshl_add_u32 v172, s13, 8, v145
	s_ashr_i32 s13, s12, 31
	s_lshl_b64 s[12:13], s[12:13], 8
	v_ashrrev_i32_e32 v158, 3, v218
	v_mov_b32_e32 v163, s13
	v_or_b32_e32 v162, s12, v134
	v_ashrrev_i32_e32 v159, 31, v158
	v_and_b32_e32 v149, 7, v218
	v_ashrrev_i32_e32 v173, 31, v172
	v_lshl_add_u64 v[174:175], v[162:163], 0, v[158:159]
	v_lshl_or_b32 v164, v149, 2, v172
	v_mov_b32_e32 v165, v173
	v_lshlrev_b64 v[160:161], 11, v[174:175]
	v_lshl_add_u64 v[160:161], v[160:161], 0, v[164:165]
	v_lshlrev_b64 v[176:177], 2, v[160:161]
	v_readlane_b32 s53, v253, 8
	v_lshl_add_u32 v166, v149, 4, v225
	v_lshlrev_b32_e32 v148, 2, v148
	v_lshl_add_u64 v[160:161], s[52:53], 0, v[176:177]
	global_load_dwordx4 v[168:171], v[160:161], off
	v_mad_u64_u32 v[158:159], s[12:13], v158, s14, v[166:167]
	v_mul_lo_u32 v128, v128, s15
	v_add3_u32 v159, v225, v148, v128
	ds_write_b32 v159, v112
	ds_write_b32 v159, v113 offset:144
	ds_write_b32 v159, v114 offset:288
	ds_write_b32 v159, v115 offset:432
	ds_write_b32 v159, v116 offset:1152
	ds_write_b32 v159, v117 offset:1296
	ds_write_b32 v159, v118 offset:1440
	ds_write_b32 v159, v119 offset:1584
	ds_write_b32 v159, v120 offset:2304
	ds_write_b32 v159, v121 offset:2448
	ds_write_b32 v159, v122 offset:2592
	ds_write_b32 v159, v123 offset:2736
	ds_write_b32 v159, v124 offset:3456
	ds_write_b32 v159, v125 offset:3600
	ds_write_b32 v159, v126 offset:3744
	ds_write_b32 v159, v127 offset:3888
	ds_write_b32 v159, v96 offset:4608
	ds_write_b32 v159, v97 offset:4752
	ds_write_b32 v159, v98 offset:4896
	ds_write_b32 v159, v99 offset:5040
	ds_write_b32 v159, v100 offset:5760
	ds_write_b32 v159, v101 offset:5904
	ds_write_b32 v159, v102 offset:6048
	ds_write_b32 v159, v103 offset:6192
	ds_write_b32 v159, v104 offset:6912
	ds_write_b32 v159, v105 offset:7056
	ds_write_b32 v159, v106 offset:7200
	ds_write_b32 v159, v107 offset:7344
	ds_write_b32 v159, v108 offset:8064
	ds_write_b32 v159, v109 offset:8208
	ds_write_b32 v159, v110 offset:8352
	ds_write_b32 v159, v111 offset:8496
	ds_write_b32 v159, v80 offset:9216
	ds_write_b32 v159, v81 offset:9360
	ds_write_b32 v159, v82 offset:9504
	ds_write_b32 v159, v83 offset:9648
	ds_write_b32 v159, v84 offset:10368
; __device__ __forceinline__ int accrow(int reg, int lh) { return (reg & 3) + 8 * (reg >> 2) + 4 * lh; }
; template <int EPI, int PN>
; __device__ void gemm_phase(const Params& p, const u16* __restrict__ A, const u16* __restrict__ Bt, int nNt, char* smem) {
;     ...
; #pragma unroll
;       for (int j = 0; j < 2; ++j) {
; #pragma unroll
;         for (int i = 0; i < 4; ++i)
; #pragma unroll
;           for (int r = 0; r < 16; ++r) *(float*)(et + (i * 32 + accrow(r, lhE)) * 144 + lrE * 4) = acc[i][j][r];
; #pragma unroll
;         for (int it = 0; it < 16; ++it) {
;           const int c = it * 64 + laneE, row = c >> 3, seg = c & 7;
;           const float4 v = *(const float4*)(et + row * 144 + seg * 16);
;           const size_t g = (row0 + row) * DM + col0 + j * 32 + seg * 4;
;           const float4 xv = *(const float4*)(p.x + g);
;           const float4 hv = make_float4(xv.x + v.x, xv.y + v.y, xv.z + v.z, xv.w + v.w);
;           *(float4*)(p.out + g) = hv;
;           uint2 hb; hb.x = pack2(hv.x, hv.y); hb.y = pack2(hv.z, hv.w);
;           *(uint2*)(p.xn + (row0 + row) * LDK + col0 + j * 32 + seg * 4) = hb;
;         }
	ds_write_b32 v159, v85 offset:10512
	ds_write_b32 v159, v86 offset:10656
	ds_write_b32 v159, v87 offset:10800
	ds_write_b32 v159, v88 offset:11520
	ds_write_b32 v159, v89 offset:11664
	ds_write_b32 v159, v90 offset:11808
	ds_write_b32 v159, v91 offset:11952
	ds_write_b32 v159, v92 offset:12672
	ds_write_b32 v159, v93 offset:12816
	ds_write_b32 v159, v94 offset:12960
	ds_write_b32 v159, v95 offset:13104
	ds_write_b32 v159, v64 offset:13824
	ds_write_b32 v159, v65 offset:13968
	ds_write_b32 v159, v66 offset:14112
	ds_write_b32 v159, v67 offset:14256
	ds_write_b32 v159, v68 offset:14976
	ds_write_b32 v159, v69 offset:15120
	ds_write_b32 v159, v70 offset:15264
	ds_write_b32 v159, v71 offset:15408
	ds_write_b32 v159, v72 offset:16128
	ds_write_b32 v159, v73 offset:16272
	ds_write_b32 v159, v74 offset:16416
	ds_write_b32 v159, v75 offset:16560
	ds_write_b32 v159, v76 offset:17280
	ds_write_b32 v159, v77 offset:17424
	ds_write_b32 v159, v78 offset:17568
	ds_write_b32 v159, v79 offset:17712
	ds_read_b128 v[66:69], v158
	v_readlane_b32 s36, v253, 23
	v_readlane_b32 s40, v253, 27
	v_readlane_b32 s41, v253, 28
	v_readlane_b32 s42, v253, 29
	v_readlane_b32 s43, v253, 30
	s_mov_b64 s[20:21], s[40:41]
	s_mov_b64 s[22:23], s[42:43]
	v_lshl_add_u64 v[64:65], s[20:21], 0, v[176:177]
	v_mov_b64_e32 v[102:103], s[22:23]
	v_lshlrev_b64 v[104:105], 1, v[172:173]
	v_lshlrev_b32_e32 v128, 3, v149
	v_readlane_b32 s54, v253, 9
	v_readlane_b32 s55, v253, 10
	v_readlane_b32 s56, v253, 11
	v_readlane_b32 s57, v253, 12
	v_readlane_b32 s58, v253, 13
	v_readlane_b32 s59, v253, 14
	v_readlane_b32 s60, v253, 15
	v_readlane_b32 s61, v253, 16
	v_readlane_b32 s62, v253, 17
	v_readlane_b32 s63, v253, 18
	v_readlane_b32 s64, v253, 19
	v_readlane_b32 s65, v253, 20
	v_readlane_b32 s66, v253, 21
	v_readlane_b32 s67, v253, 22
	v_readlane_b32 s37, v253, 24
	v_readlane_b32 s38, v253, 25
	v_readlane_b32 s39, v253, 26
	v_readlane_b32 s44, v253, 31
	v_readlane_b32 s45, v253, 32
	v_readlane_b32 s46, v253, 33
	v_readlane_b32 s47, v253, 34
	v_readlane_b32 s48, v253, 35
	v_readlane_b32 s49, v253, 36
	v_readlane_b32 s50, v253, 37
	v_readlane_b32 s51, v253, 38
	s_waitcnt vmcnt(0) lgkmcnt(0)
	v_pk_add_f32 v[66:67], v[66:67], v[168:169]
	v_pk_add_f32 v[68:69], v[68:69], v[170:171]
	global_store_dwordx4 v[64:65], v[66:69], off
	v_cvt_pk_bf16_f32 v70, v66, v67
	v_cvt_pk_bf16_f32 v71, v68, v69
	v_mad_u64_u32 v[66:67], s[12:13], v174, s2, v[102:103]
	v_mad_i32_i24 v67, v175, s2, v67
	v_lshl_add_u64 v[66:67], v[66:67], 0, v[104:105]
	v_lshl_add_u64 v[66:67], v[66:67], 0, v[128:129]
	v_add_u32_e32 v68, 64, v218
	global_store_dwordx2 v[66:67], v[70:71], off
	v_ashrrev_i32_e32 v70, 3, v68
	v_ashrrev_i32_e32 v71, 31, v70
	v_lshl_add_u64 v[74:75], v[162:163], 0, v[70:71]
	v_lshlrev_b64 v[68:69], 11, v[74:75]
	v_lshl_add_u64 v[68:69], v[68:69], 0, v[164:165]
	v_lshlrev_b64 v[76:77], 2, v[68:69]
	v_lshl_add_u64 v[68:69], s[52:53], 0, v[76:77]
	global_load_dwordx4 v[78:81], v[68:69], off
	v_mad_u64_u32 v[72:73], s[12:13], v70, s14, v[166:167]
	v_add_u32_e32 v71, 0x80, v218
	ds_read_b128 v[82:85], v72
	v_ashrrev_i32_e32 v90, 3, v71
	v_ashrrev_i32_e32 v91, 31, v90
	v_lshl_add_u64 v[94:95], v[162:163], 0, v[90:91]
	v_mad_u64_u32 v[70:71], s[12:13], v74, s2, v[102:103]
	v_lshlrev_b64 v[86:87], 11, v[94:95]
	v_mad_i32_i24 v71, v75, s2, v71
	v_lshl_add_u64 v[74:75], v[86:87], 0, v[164:165]
	v_lshl_add_u64 v[70:71], v[70:71], 0, v[104:105]
	v_lshl_add_u64 v[76:77], s[20:21], 0, v[76:77]
	v_lshlrev_b64 v[96:97], 2, v[74:75]
	v_lshl_add_u64 v[74:75], v[70:71], 0, v[128:129]
	v_lshl_add_u64 v[70:71], s[52:53], 0, v[96:97]
	v_add_u32_e32 v73, 0xc0, v218
	v_ashrrev_i32_e32 v98, 3, v73
	v_ashrrev_i32_e32 v99, 31, v98
	v_lshl_add_u64 v[106:107], v[162:163], 0, v[98:99]
	v_add_u32_e32 v73, 0x100, v218
	v_ashrrev_i32_e32 v110, 3, v73
	v_ashrrev_i32_e32 v111, 31, v110
	v_lshl_add_u64 v[114:115], v[162:163], 0, v[110:111]
	v_add_u32_e32 v73, 0x140, v218
	v_ashrrev_i32_e32 v118, 3, v73
	v_ashrrev_i32_e32 v119, 31, v118
	v_lshl_add_u64 v[122:123], v[162:163], 0, v[118:119]
	v_add_u32_e32 v73, 0x180, v218
	v_ashrrev_i32_e32 v126, 3, v73
	v_ashrrev_i32_e32 v127, 31, v126
	v_lshl_add_u64 v[172:173], v[162:163], 0, v[126:127]
	v_add_u32_e32 v73, 0x1c0, v218
	v_ashrrev_i32_e32 v176, 3, v73
	v_ashrrev_i32_e32 v177, 31, v176
	v_add_u32_e32 v73, 0x200, v218
	v_ashrrev_i32_e32 v182, 3, v73
	v_ashrrev_i32_e32 v183, 31, v182
	v_lshl_add_u64 v[186:187], v[162:163], 0, v[182:183]
	v_add_u32_e32 v73, 0x240, v218
	v_ashrrev_i32_e32 v190, 3, v73
	v_ashrrev_i32_e32 v191, 31, v190
	v_lshl_add_u64 v[194:195], v[162:163], 0, v[190:191]
	v_add_u32_e32 v73, 0x280, v218
	v_ashrrev_i32_e32 v198, 3, v73
	v_ashrrev_i32_e32 v199, 31, v198
	v_lshl_add_u64 v[202:203], v[162:163], 0, v[198:199]
	v_add_u32_e32 v73, 0x2c0, v218
	v_ashrrev_i32_e32 v206, 3, v73
	v_ashrrev_i32_e32 v207, 31, v206
	v_lshl_add_u64 v[210:211], v[162:163], 0, v[206:207]
	v_add_u32_e32 v73, 0x300, v218
	v_ashrrev_i32_e32 v214, 3, v73
	v_ashrrev_i32_e32 v215, 31, v214
	v_lshl_add_u64 v[220:221], v[162:163], 0, v[214:215]
	v_add_u32_e32 v73, 0x340, v218
	v_ashrrev_i32_e32 v238, 3, v73
	v_ashrrev_i32_e32 v239, 31, v238
	v_lshl_add_u64 v[242:243], v[162:163], 0, v[238:239]
	v_add_u32_e32 v73, 0x380, v218
	v_ashrrev_i32_e32 v246, 3, v73
	v_ashrrev_i32_e32 v247, 31, v246
	v_lshl_add_u64 v[248:249], v[162:163], 0, v[246:247]
	v_add_u32_e32 v73, 0x3c0, v218
	v_mad_u64_u32 v[218:219], s[12:13], v246, s14, v[166:167]
	v_ashrrev_i32_e32 v148, 3, v73
	v_ashrrev_i32_e32 v149, 31, v148
	v_lshl_add_u64 v[246:247], v[162:163], 0, v[148:149]
	s_waitcnt vmcnt(0) lgkmcnt(0)
; template <int EPI, int PN>
; __device__ void gemm_phase(const Params& p, const u16* __restrict__ A, const u16* __restrict__ Bt, int nNt, char* smem) {
;     ...
; #pragma unroll
;         for (int it = 0; it < 16; ++it) {
;           const int c = it * 64 + laneE, row = c >> 3, seg = c & 7;
;           const float4 v = *(const float4*)(et + row * 144 + seg * 16);
;           const size_t g = (row0 + row) * DM + col0 + j * 32 + seg * 4;
;           const float4 xv = *(const float4*)(p.x + g);
;           const float4 hv = make_float4(xv.x + v.x, xv.y + v.y, xv.z + v.z, xv.w + v.w);
;           *(float4*)(p.out + g) = hv;
;           uint2 hb; hb.x = pack2(hv.x, hv.y); hb.y = pack2(hv.z, hv.w);
;           *(uint2*)(p.xn + (row0 + row) * LDK + col0 + j * 32 + seg * 4) = hb;
;         }
	v_pk_add_f32 v[78:79], v[82:83], v[78:79]
	v_pk_add_f32 v[80:81], v[84:85], v[80:81]
	global_store_dwordx4 v[76:77], v[78:81], off
	v_lshlrev_b64 v[82:83], 11, v[106:107]
	v_lshl_add_u64 v[82:83], v[82:83], 0, v[164:165]
	v_cvt_pk_bf16_f32 v78, v78, v79
	v_cvt_pk_bf16_f32 v79, v80, v81
	global_store_dwordx2 v[74:75], v[78:79], off
	global_load_dwordx4 v[86:89], v[70:71], off
	v_mad_u64_u32 v[80:81], s[12:13], v90, s14, v[166:167]
	ds_read_b128 v[90:93], v80
	v_mad_u64_u32 v[78:79], s[12:13], v94, s2, v[102:103]
	v_mad_i32_i24 v79, v95, s2, v79
	v_lshl_add_u64 v[78:79], v[78:79], 0, v[104:105]
	v_lshl_add_u64 v[84:85], s[20:21], 0, v[96:97]
	v_lshlrev_b64 v[108:109], 2, v[82:83]
	v_lshl_add_u64 v[82:83], v[78:79], 0, v[128:129]
	v_lshl_add_u64 v[78:79], s[52:53], 0, v[108:109]
	s_waitcnt vmcnt(0) lgkmcnt(0)
	v_pk_add_f32 v[86:87], v[90:91], v[86:87]
	v_pk_add_f32 v[88:89], v[92:93], v[88:89]
	global_store_dwordx4 v[84:85], v[86:89], off
	v_lshlrev_b64 v[90:91], 11, v[114:115]
	v_lshl_add_u64 v[90:91], v[90:91], 0, v[164:165]
	v_cvt_pk_bf16_f32 v86, v86, v87
	v_cvt_pk_bf16_f32 v87, v88, v89
	global_store_dwordx2 v[82:83], v[86:87], off
	global_load_dwordx4 v[94:97], v[78:79], off
	v_mad_u64_u32 v[88:89], s[12:13], v98, s14, v[166:167]
	ds_read_b128 v[98:101], v88
	v_mad_u64_u32 v[86:87], s[12:13], v106, s2, v[102:103]
	v_mad_i32_i24 v87, v107, s2, v87
	v_lshl_add_u64 v[86:87], v[86:87], 0, v[104:105]
	v_lshl_add_u64 v[92:93], s[20:21], 0, v[108:109]
	v_lshlrev_b64 v[116:117], 2, v[90:91]
	v_lshl_add_u64 v[90:91], v[86:87], 0, v[128:129]
	v_lshl_add_u64 v[86:87], s[52:53], 0, v[116:117]
	s_waitcnt vmcnt(0) lgkmcnt(0)
	v_pk_add_f32 v[94:95], v[98:99], v[94:95]
	v_pk_add_f32 v[96:97], v[100:101], v[96:97]
	global_store_dwordx4 v[92:93], v[94:97], off
	v_lshlrev_b64 v[98:99], 11, v[122:123]
	v_lshl_add_u64 v[98:99], v[98:99], 0, v[164:165]
	v_cvt_pk_bf16_f32 v94, v94, v95
	v_cvt_pk_bf16_f32 v95, v96, v97
	global_store_dwordx2 v[90:91], v[94:95], off
	global_load_dwordx4 v[106:109], v[86:87], off
	v_mad_u64_u32 v[96:97], s[12:13], v110, s14, v[166:167]
	ds_read_b128 v[110:113], v96
	v_mad_u64_u32 v[94:95], s[12:13], v114, s2, v[102:103]
	v_mad_i32_i24 v95, v115, s2, v95
	v_lshl_add_u64 v[94:95], v[94:95], 0, v[104:105]
	v_lshl_add_u64 v[100:101], s[20:21], 0, v[116:117]
	v_lshlrev_b64 v[124:125], 2, v[98:99]
	v_lshl_add_u64 v[98:99], v[94:95], 0, v[128:129]
	v_lshl_add_u64 v[94:95], s[52:53], 0, v[124:125]
	s_waitcnt vmcnt(0) lgkmcnt(0)
	v_pk_add_f32 v[106:107], v[110:111], v[106:107]
	v_pk_add_f32 v[108:109], v[112:113], v[108:109]
	global_store_dwordx4 v[100:101], v[106:109], off
	v_lshlrev_b64 v[110:111], 11, v[172:173]
	v_lshl_add_u64 v[110:111], v[110:111], 0, v[164:165]
	v_cvt_pk_bf16_f32 v106, v106, v107
	v_cvt_pk_bf16_f32 v107, v108, v109
	global_store_dwordx2 v[98:99], v[106:107], off
	global_load_dwordx4 v[114:117], v[94:95], off
	v_mad_u64_u32 v[108:109], s[12:13], v118, s14, v[166:167]
	ds_read_b128 v[118:121], v108
	v_mad_u64_u32 v[106:107], s[12:13], v122, s2, v[102:103]
	v_mad_i32_i24 v107, v123, s2, v107
	v_lshl_add_u64 v[106:107], v[106:107], 0, v[104:105]
	v_lshl_add_u64 v[112:113], s[20:21], 0, v[124:125]
	v_lshlrev_b64 v[174:175], 2, v[110:111]
	v_lshl_add_u64 v[110:111], v[106:107], 0, v[128:129]
	v_lshl_add_u64 v[106:107], s[52:53], 0, v[174:175]
	s_waitcnt vmcnt(0) lgkmcnt(0)
	v_pk_add_f32 v[114:115], v[118:119], v[114:115]
	v_pk_add_f32 v[116:117], v[120:121], v[116:117]
	global_store_dwordx4 v[112:113], v[114:117], off
	v_lshl_add_u64 v[120:121], s[20:21], 0, v[174:175]
	s_nop 0
	v_cvt_pk_bf16_f32 v114, v114, v115
	v_cvt_pk_bf16_f32 v115, v116, v117
	global_store_dwordx2 v[110:111], v[114:115], off
	global_load_dwordx4 v[122:125], v[106:107], off
	v_mad_u64_u32 v[116:117], s[12:13], v126, s14, v[166:167]
	ds_read_b128 v[168:171], v116
	v_lshl_add_u64 v[126:127], v[162:163], 0, v[176:177]
	v_mad_u64_u32 v[114:115], s[12:13], v172, s2, v[102:103]
	v_lshlrev_b64 v[118:119], 11, v[126:127]
	v_mad_i32_i24 v115, v173, s2, v115
	v_lshl_add_u64 v[118:119], v[118:119], 0, v[164:165]
	v_lshl_add_u64 v[114:115], v[114:115], 0, v[104:105]
	v_lshlrev_b64 v[178:179], 2, v[118:119]
	v_lshl_add_u64 v[118:119], v[114:115], 0, v[128:129]
	v_lshl_add_u64 v[114:115], s[52:53], 0, v[178:179]
	v_mad_u64_u32 v[162:163], s[12:13], v248, s2, v[102:103]
	v_mad_i32_i24 v163, v249, s2, v163
	v_lshl_add_u64 v[162:163], v[162:163], 0, v[104:105]
	s_waitcnt vmcnt(0) lgkmcnt(0)
	v_pk_add_f32 v[122:123], v[168:169], v[122:123]
	v_pk_add_f32 v[124:125], v[170:171], v[124:125]
	global_store_dwordx4 v[120:121], v[122:125], off
	v_lshlrev_b64 v[168:169], 11, v[186:187]
	s_nop 0
	v_cvt_pk_bf16_f32 v122, v122, v123
	v_cvt_pk_bf16_f32 v123, v124, v125
	global_store_dwordx2 v[118:119], v[122:123], off
	global_load_dwordx4 v[170:173], v[114:115], off
	v_mad_u64_u32 v[124:125], s[12:13], v176, s14, v[166:167]
	ds_read_b128 v[174:177], v124
	v_mad_u64_u32 v[122:123], s[12:13], v126, s2, v[102:103]
	v_mad_i32_i24 v123, v127, s2, v123
	v_lshl_add_u64 v[126:127], v[168:169], 0, v[164:165]
	v_lshl_add_u64 v[122:123], v[122:123], 0, v[104:105]
	v_lshl_add_u64 v[168:169], s[20:21], 0, v[178:179]
	v_lshlrev_b64 v[188:189], 2, v[126:127]
	v_lshl_add_u64 v[126:127], v[122:123], 0, v[128:129]
	v_lshl_add_u64 v[122:123], s[52:53], 0, v[188:189]
	s_waitcnt vmcnt(0) lgkmcnt(0)
; template <int EPI, int PN>
; __device__ void gemm_phase(const Params& p, const u16* __restrict__ A, const u16* __restrict__ Bt, int nNt, char* smem) {
;     ...
; #pragma unroll
;         for (int it = 0; it < 16; ++it) {
;           const int c = it * 64 + laneE, row = c >> 3, seg = c & 7;
;           const float4 v = *(const float4*)(et + row * 144 + seg * 16);
;           const size_t g = (row0 + row) * DM + col0 + j * 32 + seg * 4;
;           const float4 xv = *(const float4*)(p.x + g);
;           const float4 hv = make_float4(xv.x + v.x, xv.y + v.y, xv.z + v.z, xv.w + v.w);
;           *(float4*)(p.out + g) = hv;
;           uint2 hb; hb.x = pack2(hv.x, hv.y); hb.y = pack2(hv.z, hv.w);
;           *(uint2*)(p.xn + (row0 + row) * LDK + col0 + j * 32 + seg * 4) = hb;
;         }
	v_pk_add_f32 v[170:171], v[174:175], v[170:171]
	v_pk_add_f32 v[172:173], v[176:177], v[172:173]
	global_store_dwordx4 v[168:169], v[170:173], off
	v_lshlrev_b64 v[174:175], 11, v[194:195]
	v_lshl_add_u64 v[174:175], v[174:175], 0, v[164:165]
	v_cvt_pk_bf16_f32 v170, v170, v171
	v_cvt_pk_bf16_f32 v171, v172, v173
	global_store_dwordx2 v[126:127], v[170:171], off
	global_load_dwordx4 v[178:181], v[122:123], off
	v_mad_u64_u32 v[172:173], s[12:13], v182, s14, v[166:167]
	ds_read_b128 v[182:185], v172
	v_mad_u64_u32 v[170:171], s[12:13], v186, s2, v[102:103]
	v_mad_i32_i24 v171, v187, s2, v171
	v_lshl_add_u64 v[170:171], v[170:171], 0, v[104:105]
	v_lshl_add_u64 v[176:177], s[20:21], 0, v[188:189]
	v_lshlrev_b64 v[196:197], 2, v[174:175]
	v_lshl_add_u64 v[174:175], v[170:171], 0, v[128:129]
	v_lshl_add_u64 v[170:171], s[52:53], 0, v[196:197]
	s_waitcnt vmcnt(0) lgkmcnt(0)
	v_pk_add_f32 v[178:179], v[182:183], v[178:179]
	v_pk_add_f32 v[180:181], v[184:185], v[180:181]
	global_store_dwordx4 v[176:177], v[178:181], off
	v_lshlrev_b64 v[182:183], 11, v[202:203]
	v_lshl_add_u64 v[182:183], v[182:183], 0, v[164:165]
	v_cvt_pk_bf16_f32 v178, v178, v179
	v_cvt_pk_bf16_f32 v179, v180, v181
	global_store_dwordx2 v[174:175], v[178:179], off
	global_load_dwordx4 v[186:189], v[170:171], off
	v_mad_u64_u32 v[180:181], s[12:13], v190, s14, v[166:167]
	ds_read_b128 v[190:193], v180
	v_mad_u64_u32 v[178:179], s[12:13], v194, s2, v[102:103]
	v_mad_i32_i24 v179, v195, s2, v179
	v_lshl_add_u64 v[178:179], v[178:179], 0, v[104:105]
	v_lshl_add_u64 v[184:185], s[20:21], 0, v[196:197]
	v_lshlrev_b64 v[204:205], 2, v[182:183]
	v_lshl_add_u64 v[182:183], v[178:179], 0, v[128:129]
	v_lshl_add_u64 v[178:179], s[52:53], 0, v[204:205]
	s_waitcnt vmcnt(0) lgkmcnt(0)
	v_pk_add_f32 v[186:187], v[190:191], v[186:187]
	v_pk_add_f32 v[188:189], v[192:193], v[188:189]
	global_store_dwordx4 v[184:185], v[186:189], off
	v_lshlrev_b64 v[190:191], 11, v[210:211]
	v_lshl_add_u64 v[190:191], v[190:191], 0, v[164:165]
	v_cvt_pk_bf16_f32 v186, v186, v187
	v_cvt_pk_bf16_f32 v187, v188, v189
	global_store_dwordx2 v[182:183], v[186:187], off
	global_load_dwordx4 v[194:197], v[178:179], off
	v_mad_u64_u32 v[188:189], s[12:13], v198, s14, v[166:167]
	ds_read_b128 v[198:201], v188
	v_mad_u64_u32 v[186:187], s[12:13], v202, s2, v[102:103]
	v_mad_i32_i24 v187, v203, s2, v187
	v_lshl_add_u64 v[186:187], v[186:187], 0, v[104:105]
	v_lshl_add_u64 v[192:193], s[20:21], 0, v[204:205]
	v_lshlrev_b64 v[212:213], 2, v[190:191]
	v_lshl_add_u64 v[190:191], v[186:187], 0, v[128:129]
	v_lshl_add_u64 v[186:187], s[52:53], 0, v[212:213]
	s_waitcnt vmcnt(0) lgkmcnt(0)
	v_pk_add_f32 v[194:195], v[198:199], v[194:195]
	v_pk_add_f32 v[196:197], v[200:201], v[196:197]
	global_store_dwordx4 v[192:193], v[194:197], off
	v_lshlrev_b64 v[198:199], 11, v[220:221]
	v_lshl_add_u64 v[198:199], v[198:199], 0, v[164:165]
	v_cvt_pk_bf16_f32 v194, v194, v195
	v_cvt_pk_bf16_f32 v195, v196, v197
	global_store_dwordx2 v[190:191], v[194:195], off
	global_load_dwordx4 v[202:205], v[186:187], off
	v_mad_u64_u32 v[196:197], s[12:13], v206, s14, v[166:167]
	ds_read_b128 v[206:209], v196
	v_mad_u64_u32 v[194:195], s[12:13], v210, s2, v[102:103]
	v_mad_i32_i24 v195, v211, s2, v195
	v_lshl_add_u64 v[194:195], v[194:195], 0, v[104:105]
	v_lshl_add_u64 v[200:201], s[20:21], 0, v[212:213]
	v_lshlrev_b64 v[222:223], 2, v[198:199]
	v_lshl_add_u64 v[198:199], v[194:195], 0, v[128:129]
	v_lshl_add_u64 v[194:195], s[52:53], 0, v[222:223]
	s_waitcnt vmcnt(0) lgkmcnt(0)
	v_pk_add_f32 v[202:203], v[206:207], v[202:203]
	v_pk_add_f32 v[204:205], v[208:209], v[204:205]
	global_store_dwordx4 v[200:201], v[202:205], off
	v_lshlrev_b64 v[206:207], 11, v[242:243]
	v_lshl_add_u64 v[206:207], v[206:207], 0, v[164:165]
	v_cvt_pk_bf16_f32 v202, v202, v203
	v_cvt_pk_bf16_f32 v203, v204, v205
	global_store_dwordx2 v[198:199], v[202:203], off
	global_load_dwordx4 v[210:213], v[194:195], off
	v_mad_u64_u32 v[204:205], s[12:13], v214, s14, v[166:167]
	ds_read_b128 v[214:217], v204
	v_mad_u64_u32 v[202:203], s[12:13], v220, s2, v[102:103]
	v_mad_i32_i24 v203, v221, s2, v203
	v_lshl_add_u64 v[202:203], v[202:203], 0, v[104:105]
	v_lshl_add_u64 v[208:209], s[20:21], 0, v[222:223]
	v_lshlrev_b64 v[244:245], 2, v[206:207]
	v_lshl_add_u64 v[206:207], v[202:203], 0, v[128:129]
	v_lshl_add_u64 v[202:203], s[52:53], 0, v[244:245]
	s_waitcnt vmcnt(0) lgkmcnt(0)
	v_pk_add_f32 v[210:211], v[214:215], v[210:211]
	v_pk_add_f32 v[212:213], v[216:217], v[212:213]
	global_store_dwordx4 v[208:209], v[210:213], off
	v_lshlrev_b64 v[214:215], 11, v[248:249]
	v_lshl_add_u64 v[214:215], v[214:215], 0, v[164:165]
	v_cvt_pk_bf16_f32 v210, v210, v211
	v_cvt_pk_bf16_f32 v211, v212, v213
	global_store_dwordx2 v[206:207], v[210:211], off
	global_load_dwordx4 v[220:223], v[202:203], off
	v_mad_u64_u32 v[212:213], s[12:13], v238, s14, v[166:167]
	ds_read_b128 v[238:241], v212
	v_mad_u64_u32 v[210:211], s[12:13], v242, s2, v[102:103]
	v_mad_i32_i24 v211, v243, s2, v211
	v_lshl_add_u64 v[210:211], v[210:211], 0, v[104:105]
	v_lshl_add_u64 v[216:217], s[20:21], 0, v[244:245]
	ds_read_b128 v[242:245], v218
	v_lshlrev_b64 v[250:251], 2, v[214:215]
	v_lshl_add_u64 v[214:215], v[210:211], 0, v[128:129]
	v_lshl_add_u64 v[210:211], s[52:53], 0, v[250:251]
	v_mad_u64_u32 v[102:103], s[12:13], v246, s2, v[102:103]
	v_mad_i32_i24 v103, v247, s2, v103
	v_lshl_add_u64 v[102:103], v[102:103], 0, v[104:105]
	v_lshl_add_u64 v[102:103], v[102:103], 0, v[128:129]
	s_waitcnt vmcnt(0) lgkmcnt(1)
; __device__ __forceinline__ int accrow(int reg, int lh) { return (reg & 3) + 8 * (reg >> 2) + 4 * lh; }
; template <int EPI, int PN>
; __device__ void gemm_phase(const Params& p, const u16* __restrict__ A, const u16* __restrict__ Bt, int nNt, char* smem) {
;     ...
; #pragma unroll
;       for (int j = 0; j < 2; ++j) {
; #pragma unroll
;         for (int i = 0; i < 4; ++i)
; #pragma unroll
;           for (int r = 0; r < 16; ++r) *(float*)(et + (i * 32 + accrow(r, lhE)) * 144 + lrE * 4) = acc[i][j][r];
; #pragma unroll
;         for (int it = 0; it < 16; ++it) {
;           const int c = it * 64 + laneE, row = c >> 3, seg = c & 7;
;           const float4 v = *(const float4*)(et + row * 144 + seg * 16);
;           const size_t g = (row0 + row) * DM + col0 + j * 32 + seg * 4;
;           const float4 xv = *(const float4*)(p.x + g);
;           const float4 hv = make_float4(xv.x + v.x, xv.y + v.y, xv.z + v.z, xv.w + v.w);
;           *(float4*)(p.out + g) = hv;
;           uint2 hb; hb.x = pack2(hv.x, hv.y); hb.y = pack2(hv.z, hv.w);
;           *(uint2*)(p.xn + (row0 + row) * LDK + col0 + j * 32 + seg * 4) = hb;
;         }
	v_pk_add_f32 v[220:221], v[238:239], v[220:221]
	v_pk_add_f32 v[222:223], v[240:241], v[222:223]
	global_store_dwordx4 v[216:217], v[220:223], off
	s_nop 1
	v_cvt_pk_bf16_f32 v220, v220, v221
	v_cvt_pk_bf16_f32 v221, v222, v223
	global_store_dwordx2 v[214:215], v[220:221], off
	global_load_dwordx4 v[238:241], v[210:211], off
	v_lshlrev_b64 v[220:221], 11, v[246:247]
	v_lshl_add_u64 v[164:165], v[220:221], 0, v[164:165]
	v_lshlrev_b64 v[248:249], 2, v[164:165]
	v_lshl_add_u64 v[222:223], s[20:21], 0, v[250:251]
	v_lshl_add_u64 v[220:221], v[162:163], 0, v[128:129]
	v_lshl_add_u64 v[164:165], s[52:53], 0, v[248:249]
	v_lshl_add_u64 v[104:105], s[20:21], 0, v[248:249]
	s_waitcnt vmcnt(0) lgkmcnt(0)
	v_pk_add_f32 v[238:239], v[242:243], v[238:239]
	v_pk_add_f32 v[240:241], v[244:245], v[240:241]
	v_cvt_pk_bf16_f32 v162, v238, v239
	v_cvt_pk_bf16_f32 v163, v240, v241
	global_store_dwordx4 v[222:223], v[238:241], off
	global_store_dwordx2 v[220:221], v[162:163], off
	global_load_dwordx4 v[238:241], v[164:165], off
	v_mad_u64_u32 v[162:163], s[12:13], v148, s14, v[166:167]
	ds_read_b128 v[242:245], v162
	v_readlane_b32 s12, v254, 28
	s_add_i32 s16, s16, s12
	s_ashr_i32 s12, s16, 31
	s_lshr_b32 s12, s12, 27
	s_add_i32 s12, s16, s12
	s_ashr_i32 s12, s12, 5
	s_lshl_b32 s12, s12, 3
	v_readlane_b32 s13, v254, 24
	s_or_b32 s17, s12, s13
	s_cmp_gt_i32 s17, 31
	s_waitcnt vmcnt(0) lgkmcnt(0)
	v_pk_add_f32 v[238:239], v[242:243], v[238:239]
	v_pk_add_f32 v[240:241], v[244:245], v[240:241]
	v_cvt_pk_bf16_f32 v148, v238, v239
	v_cvt_pk_bf16_f32 v149, v240, v241
	global_store_dwordx4 v[104:105], v[238:241], off
	global_store_dwordx2 v[102:103], v[148:149], off
	global_load_dwordx4 v[238:241], v[160:161], off offset:128
	ds_write_b32 v159, v48
	ds_write_b32 v159, v49 offset:144
	ds_write_b32 v159, v50 offset:288
	ds_write_b32 v159, v51 offset:432
	ds_write_b32 v159, v52 offset:1152
	ds_write_b32 v159, v53 offset:1296
	ds_write_b32 v159, v54 offset:1440
	ds_write_b32 v159, v55 offset:1584
	ds_write_b32 v159, v56 offset:2304
	ds_write_b32 v159, v57 offset:2448
	ds_write_b32 v159, v58 offset:2592
	ds_write_b32 v159, v59 offset:2736
	ds_write_b32 v159, v60 offset:3456
	ds_write_b32 v159, v61 offset:3600
	ds_write_b32 v159, v62 offset:3744
	ds_write_b32 v159, v63 offset:3888
	ds_write_b32 v159, v32 offset:4608
	ds_write_b32 v159, v33 offset:4752
	ds_write_b32 v159, v34 offset:4896
	ds_write_b32 v159, v35 offset:5040
	ds_write_b32 v159, v36 offset:5760
	ds_write_b32 v159, v37 offset:5904
	ds_write_b32 v159, v38 offset:6048
	ds_write_b32 v159, v39 offset:6192
	ds_write_b32 v159, v40 offset:6912
	ds_write_b32 v159, v41 offset:7056
	ds_write_b32 v159, v42 offset:7200
	ds_write_b32 v159, v43 offset:7344
	ds_write_b32 v159, v44 offset:8064
	ds_write_b32 v159, v45 offset:8208
	ds_write_b32 v159, v46 offset:8352
	ds_write_b32 v159, v47 offset:8496
	ds_write_b32 v159, v16 offset:9216
	ds_write_b32 v159, v17 offset:9360
	ds_write_b32 v159, v18 offset:9504
	ds_write_b32 v159, v19 offset:9648
	ds_write_b32 v159, v20 offset:10368
	ds_write_b32 v159, v21 offset:10512
	ds_write_b32 v159, v22 offset:10656
	ds_write_b32 v159, v23 offset:10800
	ds_write_b32 v159, v24 offset:11520
	ds_write_b32 v159, v25 offset:11664
	ds_write_b32 v159, v26 offset:11808
	ds_write_b32 v159, v27 offset:11952
	ds_write_b32 v159, v28 offset:12672
	ds_write_b32 v159, v29 offset:12816
	ds_write_b32 v159, v30 offset:12960
	ds_write_b32 v159, v31 offset:13104
	ds_write_b32 v159, v0 offset:13824
	ds_write_b32 v159, v1 offset:13968
	ds_write_b32 v159, v2 offset:14112
	ds_write_b32 v159, v3 offset:14256
	ds_write_b32 v159, v4 offset:14976
	ds_write_b32 v159, v5 offset:15120
	ds_write_b32 v159, v6 offset:15264
	ds_write_b32 v159, v7 offset:15408
	ds_write_b32 v159, v8 offset:16128
	ds_write_b32 v159, v9 offset:16272
	ds_write_b32 v159, v10 offset:16416
	ds_write_b32 v159, v11 offset:16560
	ds_write_b32 v159, v12 offset:17280
	ds_write_b32 v159, v13 offset:17424
	ds_write_b32 v159, v14 offset:17568
	ds_write_b32 v159, v15 offset:17712
	ds_read_b128 v[0:3], v158
	ds_read_b128 v[4:7], v72
	s_waitcnt vmcnt(0) lgkmcnt(1)
	v_pk_add_f32 v[0:1], v[0:1], v[238:239]
	v_pk_add_f32 v[2:3], v[2:3], v[240:241]
	global_store_dwordx4 v[64:65], v[0:3], off offset:128
	s_nop 1
	v_cvt_pk_bf16_f32 v0, v0, v1
	v_cvt_pk_bf16_f32 v1, v2, v3
	global_store_dwordx2 v[66:67], v[0:1], off offset:64
	global_load_dwordx4 v[0:3], v[68:69], off offset:128
	s_waitcnt vmcnt(0) lgkmcnt(0)
	v_pk_add_f32 v[0:1], v[4:5], v[0:1]
	v_pk_add_f32 v[2:3], v[6:7], v[2:3]
	global_store_dwordx4 v[76:77], v[0:3], off offset:128
	ds_read_b128 v[4:7], v80
	s_nop 0
	v_cvt_pk_bf16_f32 v0, v0, v1
	v_cvt_pk_bf16_f32 v1, v2, v3
	global_store_dwordx2 v[74:75], v[0:1], off offset:64
	global_load_dwordx4 v[0:3], v[70:71], off offset:128
	s_waitcnt vmcnt(0) lgkmcnt(0)
; template <int EPI, int PN>
; __device__ void gemm_phase(const Params& p, const u16* __restrict__ A, const u16* __restrict__ Bt, int nNt, char* smem) {
;     ...
; #pragma unroll
;         for (int it = 0; it < 16; ++it) {
;           const int c = it * 64 + laneE, row = c >> 3, seg = c & 7;
;           const float4 v = *(const float4*)(et + row * 144 + seg * 16);
;           const size_t g = (row0 + row) * DM + col0 + j * 32 + seg * 4;
;           const float4 xv = *(const float4*)(p.x + g);
;           const float4 hv = make_float4(xv.x + v.x, xv.y + v.y, xv.z + v.z, xv.w + v.w);
;           *(float4*)(p.out + g) = hv;
;           uint2 hb; hb.x = pack2(hv.x, hv.y); hb.y = pack2(hv.z, hv.w);
;           *(uint2*)(p.xn + (row0 + row) * LDK + col0 + j * 32 + seg * 4) = hb;
;         }
	v_pk_add_f32 v[0:1], v[4:5], v[0:1]
	v_pk_add_f32 v[2:3], v[6:7], v[2:3]
	global_store_dwordx4 v[84:85], v[0:3], off offset:128
	ds_read_b128 v[4:7], v88
	s_nop 0
	v_cvt_pk_bf16_f32 v0, v0, v1
	v_cvt_pk_bf16_f32 v1, v2, v3
	global_store_dwordx2 v[82:83], v[0:1], off offset:64
	global_load_dwordx4 v[0:3], v[78:79], off offset:128
	s_waitcnt vmcnt(0) lgkmcnt(0)
	v_pk_add_f32 v[0:1], v[4:5], v[0:1]
	v_pk_add_f32 v[2:3], v[6:7], v[2:3]
	global_store_dwordx4 v[92:93], v[0:3], off offset:128
	ds_read_b128 v[4:7], v96
	s_nop 0
	v_cvt_pk_bf16_f32 v0, v0, v1
	v_cvt_pk_bf16_f32 v1, v2, v3
	global_store_dwordx2 v[90:91], v[0:1], off offset:64
	global_load_dwordx4 v[0:3], v[86:87], off offset:128
	s_waitcnt vmcnt(0) lgkmcnt(0)
	v_pk_add_f32 v[0:1], v[4:5], v[0:1]
	v_pk_add_f32 v[2:3], v[6:7], v[2:3]
	global_store_dwordx4 v[100:101], v[0:3], off offset:128
	ds_read_b128 v[4:7], v108
	s_nop 0
	v_cvt_pk_bf16_f32 v0, v0, v1
	v_cvt_pk_bf16_f32 v1, v2, v3
	global_store_dwordx2 v[98:99], v[0:1], off offset:64
	global_load_dwordx4 v[0:3], v[94:95], off offset:128
	s_waitcnt vmcnt(0) lgkmcnt(0)
	v_pk_add_f32 v[0:1], v[4:5], v[0:1]
	v_pk_add_f32 v[2:3], v[6:7], v[2:3]
	global_store_dwordx4 v[112:113], v[0:3], off offset:128
	ds_read_b128 v[4:7], v116
	s_nop 0
	v_cvt_pk_bf16_f32 v0, v0, v1
	v_cvt_pk_bf16_f32 v1, v2, v3
	global_store_dwordx2 v[110:111], v[0:1], off offset:64
	global_load_dwordx4 v[0:3], v[106:107], off offset:128
	s_waitcnt vmcnt(0) lgkmcnt(0)
	v_pk_add_f32 v[0:1], v[4:5], v[0:1]
	v_pk_add_f32 v[2:3], v[6:7], v[2:3]
	global_store_dwordx4 v[120:121], v[0:3], off offset:128
	ds_read_b128 v[4:7], v124
	s_nop 0
	v_cvt_pk_bf16_f32 v0, v0, v1
	v_cvt_pk_bf16_f32 v1, v2, v3
	global_store_dwordx2 v[118:119], v[0:1], off offset:64
	global_load_dwordx4 v[0:3], v[114:115], off offset:128
	s_waitcnt vmcnt(0) lgkmcnt(0)
	v_pk_add_f32 v[0:1], v[4:5], v[0:1]
	v_pk_add_f32 v[2:3], v[6:7], v[2:3]
	global_store_dwordx4 v[168:169], v[0:3], off offset:128
	ds_read_b128 v[4:7], v172
	s_nop 0
	v_cvt_pk_bf16_f32 v0, v0, v1
	v_cvt_pk_bf16_f32 v1, v2, v3
	global_store_dwordx2 v[126:127], v[0:1], off offset:64
	global_load_dwordx4 v[0:3], v[122:123], off offset:128
	s_waitcnt vmcnt(0) lgkmcnt(0)
	v_pk_add_f32 v[0:1], v[4:5], v[0:1]
	v_pk_add_f32 v[2:3], v[6:7], v[2:3]
	global_store_dwordx4 v[176:177], v[0:3], off offset:128
	ds_read_b128 v[4:7], v180
	s_nop 0
	v_cvt_pk_bf16_f32 v0, v0, v1
	v_cvt_pk_bf16_f32 v1, v2, v3
	global_store_dwordx2 v[174:175], v[0:1], off offset:64
	global_load_dwordx4 v[0:3], v[170:171], off offset:128
	s_waitcnt vmcnt(0) lgkmcnt(0)
	v_pk_add_f32 v[0:1], v[4:5], v[0:1]
	v_pk_add_f32 v[2:3], v[6:7], v[2:3]
	global_store_dwordx4 v[184:185], v[0:3], off offset:128
	ds_read_b128 v[4:7], v188
	s_nop 0
	v_cvt_pk_bf16_f32 v0, v0, v1
	v_cvt_pk_bf16_f32 v1, v2, v3
	global_store_dwordx2 v[182:183], v[0:1], off offset:64
	global_load_dwordx4 v[0:3], v[178:179], off offset:128
	s_waitcnt vmcnt(0) lgkmcnt(0)
	v_pk_add_f32 v[0:1], v[4:5], v[0:1]
	v_pk_add_f32 v[2:3], v[6:7], v[2:3]
	global_store_dwordx4 v[192:193], v[0:3], off offset:128
	ds_read_b128 v[4:7], v196
	s_nop 0
	v_cvt_pk_bf16_f32 v0, v0, v1
	v_cvt_pk_bf16_f32 v1, v2, v3
	global_store_dwordx2 v[190:191], v[0:1], off offset:64
	global_load_dwordx4 v[0:3], v[186:187], off offset:128
	s_waitcnt vmcnt(0) lgkmcnt(0)
	v_pk_add_f32 v[0:1], v[4:5], v[0:1]
	v_pk_add_f32 v[2:3], v[6:7], v[2:3]
	global_store_dwordx4 v[200:201], v[0:3], off offset:128
	ds_read_b128 v[4:7], v204
	s_nop 0
	v_cvt_pk_bf16_f32 v0, v0, v1
	v_cvt_pk_bf16_f32 v1, v2, v3
	global_store_dwordx2 v[198:199], v[0:1], off offset:64
	global_load_dwordx4 v[0:3], v[194:195], off offset:128
	s_waitcnt vmcnt(0) lgkmcnt(0)
	v_pk_add_f32 v[0:1], v[4:5], v[0:1]
	v_pk_add_f32 v[2:3], v[6:7], v[2:3]
	global_store_dwordx4 v[208:209], v[0:3], off offset:128
	ds_read_b128 v[4:7], v212
	s_nop 0
	v_cvt_pk_bf16_f32 v0, v0, v1
	v_cvt_pk_bf16_f32 v1, v2, v3
	global_store_dwordx2 v[206:207], v[0:1], off offset:64
	global_load_dwordx4 v[0:3], v[202:203], off offset:128
	s_waitcnt vmcnt(0) lgkmcnt(0)
	v_pk_add_f32 v[0:1], v[4:5], v[0:1]
	v_pk_add_f32 v[2:3], v[6:7], v[2:3]
	global_store_dwordx4 v[216:217], v[0:3], off offset:128
	ds_read_b128 v[4:7], v218
	s_nop 0
	v_cvt_pk_bf16_f32 v0, v0, v1
	v_cvt_pk_bf16_f32 v1, v2, v3
	global_store_dwordx2 v[214:215], v[0:1], off offset:64
	global_load_dwordx4 v[0:3], v[210:211], off offset:128
	s_waitcnt vmcnt(0) lgkmcnt(0)
	v_pk_add_f32 v[0:1], v[4:5], v[0:1]
	v_pk_add_f32 v[2:3], v[6:7], v[2:3]
	global_store_dwordx4 v[222:223], v[0:3], off offset:128
	ds_read_b128 v[4:7], v162
	s_nop 0
	v_cvt_pk_bf16_f32 v0, v0, v1
	v_cvt_pk_bf16_f32 v1, v2, v3
	global_store_dwordx2 v[220:221], v[0:1], off offset:64
	global_load_dwordx4 v[0:3], v[164:165], off offset:128
	s_waitcnt vmcnt(0) lgkmcnt(0)
	v_pk_add_f32 v[0:1], v[4:5], v[0:1]
	v_pk_add_f32 v[2:3], v[6:7], v[2:3]
	global_store_dwordx4 v[104:105], v[0:3], off offset:128
	s_nop 1
	v_cvt_pk_bf16_f32 v0, v0, v1
	v_cvt_pk_bf16_f32 v1, v2, v3
	global_store_dwordx2 v[102:103], v[0:1], off offset:64
	s_barrier
	s_cbranch_scc0 .LBB0_665
